# attention loop wave priority experiment 17a (a: no static prio, b: prio for waves 0-3 instead of 4-7)
# speedup vs baseline: 1.0130x; 1.0052x over previous
; #define SLOAD(i, k0) do { sr_[i].vs0 = LD8(&Vh[(long)((k0) + sr) * LDK + sc]); sr_[i].vs1 = LD8(&Vh[(long)((k0) + 32 + sr) * LDK + sc]); \
;     sr_[i].ks0 = LD8(&Kh[(long)((k0) + sr) * LDK + sc]); sr_[i].ks1 = LD8(&Kh[(long)((k0) + 32 + sr) * LDK + sc]); } while (0)
; #define SWRITE(b, i) do { *(bf16x8*)((char*)V_lds + (b) * SHM_V + vst0) = sr_[i].vs0;          \
;     *(bf16x8*)((char*)V_lds + (b) * SHM_V + vst1) = sr_[i].vs1; int kc = sc * 2;               \
;     *(bf16x8*)((char*)K_lds + (b) * SHM_K + KSWZ(sr, kc)) = sr_[i].ks0;                       \
;     *(bf16x8*)((char*)K_lds + (b) * SHM_K + KSWZ(32 + sr, kc)) = sr_[i].ks1; } while (0)
; #define SWAIT() asm volatile("s_waitcnt vmcnt(4)" ::: "memory")
; __device__ __forceinline__ void attn_body(const bf16_t* __restrict__ Qb, const bf16_t* __restrict__ Kh, const bf16_t* __restrict__ Vh, const bf16_t* __restrict__ Zb, ...
;     ...
;     SLOAD(SE, 2 * KVBLK);
;     SWAIT(); SWRITE(1, SO); __syncthreads();
;     if (__builtin_amdgcn_readfirstlane(tid) >= 256) __builtin_amdgcn_s_setprio(1);
.LBB0_487:
	v_add_u32_e32 v32, 0x80, v186
	v_mad_i64_i32 v[32:33], s[42:43], v32, s31, 0
	v_add_u32_e32 v34, 0xa0, v186
	v_or_b32_e32 v32, v32, v198
	v_mad_i64_i32 v[34:35], s[42:43], v34, s31, 0
	v_lshl_add_u64 v[32:33], v[32:33], 1, s[20:21]
	v_or_b32_e32 v34, v34, v198
	v_lshl_add_u64 v[34:35], v[34:35], 1, s[20:21]
	global_load_dwordx4 v[144:147], v[32:33], off offset:2560
	global_load_dwordx4 v[148:151], v[32:33], off offset:2048
	global_load_dwordx4 v[156:159], v[34:35], off offset:2560
	global_load_dwordx4 v[152:155], v[34:35], off offset:2048
	s_waitcnt vmcnt(4)
	v_readfirstlane_b32 s23, v200
	v_ashrrev_i32_e32 v187, 31, v186
	s_cmpk_lt_i32 s23, 0x100
	ds_write_b128 v207, v[16:19] offset:16384
	ds_write_b128 v208, v[28:31] offset:16384
	ds_write_b128 v209, v[20:23] offset:49152
	ds_write_b128 v210, v[24:27] offset:49152
	s_waitcnt lgkmcnt(0)
	s_barrier
	s_cbranch_scc1 .LBB0_489
	s_setprio 0
